# MLP-up epilogue: activation stores marked sc1 (write-through) so the grid barrier's L2 write-back has little left to do
# baseline (speedup 1.0000x reference)
.LBB0_986:
	s_andn2_b64 vcc, exec, s[8:9]
	s_cbranch_vccnz .LBB0_988
	v_add_u32_e32 v150, s10, v155
	v_readlane_b32 s8, v254, 63
	v_ashrrev_i32_e32 v151, 31, v150
	v_readlane_b32 s9, v255, 0
	v_lshl_or_b32 v144, s44, 8, v138
	v_ashrrev_i32_e32 v145, 31, v144
	v_lshl_add_u64 v[146:147], v[150:151], 2, s[8:9]
	global_load_dword v202, v[146:147], off
	global_load_dword v203, v[146:147], off offset:64
	global_load_dword v204, v[146:147], off offset:128
	global_load_dword v205, v[146:147], off offset:192
	global_load_dword v206, v[146:147], off offset:512
	global_load_dword v207, v[146:147], off offset:576
	global_load_dword v208, v[146:147], off offset:640
	global_load_dword v209, v[146:147], off offset:704
	v_lshl_add_u64 v[148:149], v[144:145], 1, s[74:75]
	v_lshlrev_b64 v[144:145], 13, v[150:151]
	v_lshl_add_u64 v[144:145], v[148:149], 0, v[144:145]
	s_mov_b32 s3, 0x100000
	s_waitcnt vmcnt(0)
	v_fmamk_f32 v0, v202, 0x3a800000, v139
	v_rsq_f32_e32 v0, v0
	s_nop 0
	v_pk_mul_f32 v[160:161], v[128:129], v[0:1] op_sel_hi:[1,0]
	v_pk_mul_f32 v[162:163], v[126:127], v[0:1] op_sel_hi:[1,0]
	v_pk_mul_f32 v[164:165], v[124:125], v[0:1] op_sel_hi:[1,0]
	v_pk_mul_f32 v[166:167], v[122:123], v[0:1] op_sel_hi:[1,0]
	v_max_f32_e32 v160, 0, v160
	v_max_f32_e32 v151, 0, v162
	v_max_f32_e32 v159, 0, v166
	v_max_f32_e32 v162, 0, v163
	v_max_f32_e32 v163, 0, v167
	v_mul_f32_e32 v166, v160, v160
	v_max_f32_e32 v160, 0, v161
	v_max_f32_e32 v161, 0, v165
	v_mul_f32_e32 v151, v151, v151
	v_mul_f32_e32 v162, v162, v162
	v_mul_f32_e32 v163, v163, v163
	v_max_f32_e32 v164, 0, v164
	v_mul_f32_e32 v165, v160, v160
	v_mul_f32_e32 v167, v161, v161
	v_cvt_pk_bf16_f32 v160, v151, v162
	v_cvt_pk_bf16_f32 v161, v166, v165
	v_mul_f32_e32 v159, v159, v159
	v_mul_f32_e32 v164, v164, v164
	v_cvt_pk_bf16_f32 v162, v159, v163
	v_cvt_pk_bf16_f32 v163, v164, v167
	global_store_dwordx4 v[144:145], v[160:163], off sc1
	v_pk_mul_f32 v[164:165], v[116:117], v[0:1] op_sel_hi:[1,0]
	v_pk_mul_f32 v[166:167], v[114:115], v[0:1] op_sel_hi:[1,0]
	v_pk_mul_f32 v[160:161], v[120:121], v[0:1] op_sel_hi:[1,0]
	v_pk_mul_f32 v[162:163], v[118:119], v[0:1] op_sel_hi:[1,0]
	v_max_f32_e32 v160, 0, v160
	v_max_f32_e32 v0, 0, v162
	v_max_f32_e32 v159, 0, v163
	v_max_f32_e32 v162, 0, v167
	v_max_f32_e32 v163, 0, v164
	v_mul_f32_e32 v164, v160, v160
	v_max_f32_e32 v160, 0, v161
	v_max_f32_e32 v151, 0, v166
	v_mul_f32_e32 v0, v0, v0
	v_mul_f32_e32 v159, v159, v159
	v_mul_f32_e32 v162, v162, v162
	v_mul_f32_e32 v163, v163, v163
	v_max_f32_e32 v161, 0, v165
	v_mul_f32_e32 v165, v160, v160
	v_cvt_pk_bf16_f32 v160, v0, v159
	v_mul_f32_e32 v151, v151, v151
	v_mul_f32_e32 v166, v161, v161
	v_cvt_pk_bf16_f32 v161, v164, v165
	v_cvt_pk_bf16_f32 v162, v151, v162
	v_cvt_pk_bf16_f32 v163, v163, v166
	global_store_dwordx4 v[144:145], v[160:163], off offset:256 sc1
	s_nop 1
	v_or_b32_e32 v160, 16, v150
	v_ashrrev_i32_e32 v161, 31, v160
	v_lshl_add_u64 v[162:163], v[160:161], 2, s[8:9]
	v_lshlrev_b64 v[160:161], 13, v[160:161]
	v_lshl_add_u64 v[164:165], v[148:149], 0, v[160:161]
	v_fmamk_f32 v0, v203, 0x3a800000, v139
	v_rsq_f32_e32 v0, v0
	s_nop 0
	v_pk_mul_f32 v[160:161], v[112:113], v[0:1] op_sel_hi:[1,0]
	v_pk_mul_f32 v[162:163], v[110:111], v[0:1] op_sel_hi:[1,0]
	v_pk_mul_f32 v[166:167], v[108:109], v[0:1] op_sel_hi:[1,0]
	v_pk_mul_f32 v[168:169], v[106:107], v[0:1] op_sel_hi:[1,0]
	v_max_f32_e32 v160, 0, v160
	v_max_f32_e32 v151, 0, v162
	v_max_f32_e32 v159, 0, v168
	v_max_f32_e32 v162, 0, v163
	v_max_f32_e32 v163, 0, v169
	v_mul_f32_e32 v168, v160, v160
	v_max_f32_e32 v160, 0, v161
	v_max_f32_e32 v161, 0, v167
	v_mul_f32_e32 v151, v151, v151
	v_mul_f32_e32 v162, v162, v162
	v_mul_f32_e32 v163, v163, v163
	v_max_f32_e32 v166, 0, v166
	v_mul_f32_e32 v167, v160, v160
	v_mul_f32_e32 v169, v161, v161
	v_cvt_pk_bf16_f32 v160, v151, v162
	v_cvt_pk_bf16_f32 v161, v168, v167
	v_mul_f32_e32 v159, v159, v159
	v_mul_f32_e32 v166, v166, v166
	v_cvt_pk_bf16_f32 v162, v159, v163
	v_cvt_pk_bf16_f32 v163, v166, v169
	global_store_dwordx4 v[164:165], v[160:163], off sc1
	v_pk_mul_f32 v[166:167], v[100:101], v[0:1] op_sel_hi:[1,0]
	v_pk_mul_f32 v[168:169], v[98:99], v[0:1] op_sel_hi:[1,0]
	v_pk_mul_f32 v[160:161], v[104:105], v[0:1] op_sel_hi:[1,0]
	v_pk_mul_f32 v[162:163], v[102:103], v[0:1] op_sel_hi:[1,0]
	v_max_f32_e32 v160, 0, v160
	v_max_f32_e32 v0, 0, v162
	v_max_f32_e32 v159, 0, v163
	v_max_f32_e32 v162, 0, v169
	v_max_f32_e32 v163, 0, v166
	v_mul_f32_e32 v166, v160, v160
	v_max_f32_e32 v160, 0, v161
	v_max_f32_e32 v151, 0, v168
	v_mul_f32_e32 v0, v0, v0
	v_mul_f32_e32 v159, v159, v159
	v_mul_f32_e32 v162, v162, v162
	v_mul_f32_e32 v163, v163, v163
	v_max_f32_e32 v161, 0, v167
	v_mul_f32_e32 v167, v160, v160
	v_cvt_pk_bf16_f32 v160, v0, v159
	v_mul_f32_e32 v151, v151, v151
	v_mul_f32_e32 v168, v161, v161
	v_cvt_pk_bf16_f32 v161, v166, v167
	v_cvt_pk_bf16_f32 v162, v151, v162
	v_cvt_pk_bf16_f32 v163, v163, v168
	global_store_dwordx4 v[164:165], v[160:163], off offset:256 sc1
	s_nop 1
	v_or_b32_e32 v160, 32, v150
	v_ashrrev_i32_e32 v161, 31, v160
	v_lshl_add_u64 v[162:163], v[160:161], 2, s[8:9]
	v_lshlrev_b64 v[160:161], 13, v[160:161]
	v_lshl_add_u64 v[164:165], v[148:149], 0, v[160:161]
	v_or_b32_e32 v150, 48, v150
	v_fmamk_f32 v0, v204, 0x3a800000, v139
	v_rsq_f32_e32 v0, v0
	s_nop 0
	v_pk_mul_f32 v[160:161], v[96:97], v[0:1] op_sel_hi:[1,0]
	v_pk_mul_f32 v[162:163], v[94:95], v[0:1] op_sel_hi:[1,0]
	v_pk_mul_f32 v[168:169], v[90:91], v[0:1] op_sel_hi:[1,0]
	v_pk_mul_f32 v[166:167], v[92:93], v[0:1] op_sel_hi:[1,0]
	v_max_f32_e32 v151, 0, v162
	v_max_f32_e32 v162, 0, v163
	v_max_f32_e32 v163, 0, v169
	v_max_f32_e32 v160, 0, v160
	v_max_f32_e32 v159, 0, v168
	v_mul_f32_e32 v162, v162, v162
	v_mul_f32_e32 v163, v163, v163
	v_max_f32_e32 v166, 0, v166
	v_mul_f32_e32 v168, v160, v160
	v_max_f32_e32 v160, 0, v161
	v_max_f32_e32 v161, 0, v167
	v_mul_f32_e32 v151, v151, v151
	v_mul_f32_e32 v159, v159, v159
	v_mul_f32_e32 v166, v166, v166
	v_mul_f32_e32 v167, v160, v160
	v_mul_f32_e32 v169, v161, v161
	v_cvt_pk_bf16_f32 v160, v151, v162
	v_cvt_pk_bf16_f32 v161, v168, v167
	v_cvt_pk_bf16_f32 v162, v159, v163
	v_cvt_pk_bf16_f32 v163, v166, v169
	global_store_dwordx4 v[164:165], v[160:163], off sc1
	v_pk_mul_f32 v[168:169], v[82:83], v[0:1] op_sel_hi:[1,0]
	v_pk_mul_f32 v[166:167], v[84:85], v[0:1] op_sel_hi:[1,0]
	v_pk_mul_f32 v[160:161], v[88:89], v[0:1] op_sel_hi:[1,0]
	v_pk_mul_f32 v[162:163], v[86:87], v[0:1] op_sel_hi:[1,0]
	v_max_f32_e32 v151, 0, v168
	v_max_f32_e32 v0, 0, v162
	v_max_f32_e32 v162, 0, v169
	v_max_f32_e32 v160, 0, v160
	v_mul_f32_e32 v151, v151, v151
	v_max_f32_e32 v159, 0, v163
	v_mul_f32_e32 v162, v162, v162
	v_max_f32_e32 v163, 0, v166
	v_mul_f32_e32 v166, v160, v160
	v_max_f32_e32 v160, 0, v161
	v_max_f32_e32 v161, 0, v167
	v_mul_f32_e32 v0, v0, v0
	v_mul_f32_e32 v159, v159, v159
	v_mul_f32_e32 v163, v163, v163
	v_mul_f32_e32 v167, v160, v160
	v_mul_f32_e32 v168, v161, v161
	v_cvt_pk_bf16_f32 v160, v0, v159
	v_cvt_pk_bf16_f32 v161, v166, v167
	v_cvt_pk_bf16_f32 v162, v151, v162
	v_ashrrev_i32_e32 v151, 31, v150
	v_cvt_pk_bf16_f32 v163, v163, v168
	global_store_dwordx4 v[164:165], v[160:163], off offset:256 sc1
	s_nop 1
	v_lshl_add_u64 v[160:161], v[150:151], 2, s[8:9]
	v_lshlrev_b64 v[150:151], 13, v[150:151]
	v_lshl_add_u64 v[148:149], v[148:149], 0, v[150:151]
	s_mov_b64 s[8:9], 0x100000
	v_fmamk_f32 v0, v205, 0x3a800000, v139
	v_rsq_f32_e32 v0, v0
	s_nop 0
	v_pk_mul_f32 v[160:161], v[78:79], v[0:1] op_sel_hi:[1,0]
	v_pk_mul_f32 v[164:165], v[74:75], v[0:1] op_sel_hi:[1,0]
	v_max_f32_e32 v159, 0, v160
	v_max_f32_e32 v160, 0, v164
	v_pk_mul_f32 v[162:163], v[76:77], v[0:1] op_sel_hi:[1,0]
	v_mul_f32_e32 v164, v160, v160
	v_max_f32_e32 v160, 0, v161
	v_max_f32_e32 v161, 0, v165
	v_pk_mul_f32 v[150:151], v[80:81], v[0:1] op_sel_hi:[1,0]
	v_mul_f32_e32 v165, v161, v161
	v_max_f32_e32 v161, 0, v162
	v_mul_f32_e32 v160, v160, v160
	v_max_f32_e32 v150, 0, v150
	v_mul_f32_e32 v166, v161, v161
	v_max_f32_e32 v151, 0, v151
	v_max_f32_e32 v161, 0, v163
	v_mul_f32_e32 v159, v159, v159
	v_mul_f32_e32 v150, v150, v150
	v_mul_f32_e32 v151, v151, v151
	v_mul_f32_e32 v163, v161, v161
	v_cvt_pk_bf16_f32 v160, v159, v160
	v_cvt_pk_bf16_f32 v161, v150, v151
	v_cvt_pk_bf16_f32 v162, v164, v165
	v_cvt_pk_bf16_f32 v163, v166, v163
	global_store_dwordx4 v[148:149], v[160:163], off sc1
	v_pk_mul_f32 v[164:165], v[66:67], v[0:1] op_sel_hi:[1,0]
	v_pk_mul_f32 v[150:151], v[72:73], v[0:1] op_sel_hi:[1,0]
	v_pk_mul_f32 v[160:161], v[70:71], v[0:1] op_sel_hi:[1,0]
	v_pk_mul_f32 v[162:163], v[68:69], v[0:1] op_sel_hi:[1,0]
	v_max_f32_e32 v0, 0, v160
	v_max_f32_e32 v160, 0, v161
	v_max_f32_e32 v161, 0, v165
	v_max_f32_e32 v159, 0, v164
	v_mul_f32_e32 v164, v161, v161
	v_max_f32_e32 v161, 0, v162
	v_mul_f32_e32 v165, v161, v161
	v_max_f32_e32 v161, 0, v163
	v_mul_f32_e32 v160, v160, v160
	v_max_f32_e32 v150, 0, v150
	v_max_f32_e32 v151, 0, v151
	v_mul_f32_e32 v163, v161, v161
	v_mul_f32_e32 v0, v0, v0
	v_mul_f32_e32 v159, v159, v159
	v_mul_f32_e32 v150, v150, v150
	v_mul_f32_e32 v151, v151, v151
	v_cvt_pk_bf16_f32 v160, v0, v160
	v_cvt_pk_bf16_f32 v161, v150, v151
	v_cvt_pk_bf16_f32 v162, v159, v164
	v_cvt_pk_bf16_f32 v163, v165, v163
	global_store_dwordx4 v[148:149], v[160:163], off offset:256 sc1
	v_lshl_add_u64 v[148:149], v[144:145], 0, s[8:9]
	s_mov_b64 s[8:9], 0x120000
	v_fmamk_f32 v0, v206, 0x3a800000, v139
	v_rsq_f32_e32 v0, v0
	s_nop 0
	v_pk_mul_f32 v[160:161], v[62:63], v[0:1] op_sel_hi:[1,0]
	v_pk_mul_f32 v[164:165], v[58:59], v[0:1] op_sel_hi:[1,0]
	v_max_f32_e32 v159, 0, v160
	v_max_f32_e32 v160, 0, v164
	v_pk_mul_f32 v[150:151], v[64:65], v[0:1] op_sel_hi:[1,0]
	v_pk_mul_f32 v[162:163], v[60:61], v[0:1] op_sel_hi:[1,0]
	v_mul_f32_e32 v164, v160, v160
	v_max_f32_e32 v160, 0, v161
	v_max_f32_e32 v161, 0, v165
	v_mul_f32_e32 v165, v161, v161
	v_max_f32_e32 v150, 0, v150
	v_max_f32_e32 v161, 0, v162
	v_mul_f32_e32 v160, v160, v160
	v_mul_f32_e32 v150, v150, v150
	v_mul_f32_e32 v166, v161, v161
	v_max_f32_e32 v151, 0, v151
	v_max_f32_e32 v161, 0, v163
	v_mul_f32_e32 v159, v159, v159
	v_mul_f32_e32 v151, v151, v151
	v_mul_f32_e32 v163, v161, v161
	v_cvt_pk_bf16_f32 v160, v159, v160
	v_cvt_pk_bf16_f32 v161, v150, v151
	v_add_co_u32_e32 v150, vcc, s3, v144
	v_cvt_pk_bf16_f32 v162, v164, v165
	v_cvt_pk_bf16_f32 v163, v166, v163
	v_pk_mul_f32 v[164:165], v[50:51], v[0:1] op_sel_hi:[1,0]
	s_nop 0
	v_addc_co_u32_e32 v151, vcc, 0, v145, vcc
	global_store_dwordx4 v[150:151], v[160:163], off sc1
	v_pk_mul_f32 v[150:151], v[56:57], v[0:1] op_sel_hi:[1,0]
	v_max_f32_e32 v159, 0, v164
	v_pk_mul_f32 v[160:161], v[54:55], v[0:1] op_sel_hi:[1,0]
	v_pk_mul_f32 v[162:163], v[52:53], v[0:1] op_sel_hi:[1,0]
	v_max_f32_e32 v0, 0, v160
	v_max_f32_e32 v160, 0, v161
	v_max_f32_e32 v161, 0, v165
	v_mul_f32_e32 v164, v161, v161
	v_max_f32_e32 v161, 0, v162
	v_mul_f32_e32 v165, v161, v161
	v_max_f32_e32 v161, 0, v163
	v_mul_f32_e32 v160, v160, v160
	v_max_f32_e32 v150, 0, v150
	v_max_f32_e32 v151, 0, v151
	v_mul_f32_e32 v163, v161, v161
	v_mul_f32_e32 v0, v0, v0
	v_mul_f32_e32 v159, v159, v159
	v_mul_f32_e32 v150, v150, v150
	v_mul_f32_e32 v151, v151, v151
	v_cvt_pk_bf16_f32 v160, v0, v160
	v_cvt_pk_bf16_f32 v161, v150, v151
	v_cvt_pk_bf16_f32 v162, v159, v164
	v_cvt_pk_bf16_f32 v163, v165, v163
	global_store_dwordx4 v[148:149], v[160:163], off offset:256 sc1
	s_mov_b32 s3, 0x120000
	v_lshl_add_u64 v[148:149], v[144:145], 0, s[8:9]
	s_mov_b64 s[8:9], 0x140000
	v_fmamk_f32 v0, v207, 0x3a800000, v139
	v_rsq_f32_e32 v0, v0
	s_nop 0
	v_pk_mul_f32 v[160:161], v[46:47], v[0:1] op_sel_hi:[1,0]
	v_pk_mul_f32 v[164:165], v[42:43], v[0:1] op_sel_hi:[1,0]
	v_max_f32_e32 v159, 0, v160
	v_max_f32_e32 v160, 0, v164
	v_pk_mul_f32 v[150:151], v[48:49], v[0:1] op_sel_hi:[1,0]
	v_pk_mul_f32 v[162:163], v[44:45], v[0:1] op_sel_hi:[1,0]
	v_mul_f32_e32 v164, v160, v160
	v_max_f32_e32 v160, 0, v161
	v_max_f32_e32 v161, 0, v165
	v_mul_f32_e32 v165, v161, v161
	v_max_f32_e32 v150, 0, v150
	v_max_f32_e32 v161, 0, v162
	v_mul_f32_e32 v160, v160, v160
	v_mul_f32_e32 v150, v150, v150
	v_mul_f32_e32 v166, v161, v161
	v_max_f32_e32 v151, 0, v151
	v_max_f32_e32 v161, 0, v163
	v_mul_f32_e32 v159, v159, v159
	v_mul_f32_e32 v151, v151, v151
	v_mul_f32_e32 v163, v161, v161
	v_cvt_pk_bf16_f32 v160, v159, v160
	v_cvt_pk_bf16_f32 v161, v150, v151
	v_add_co_u32_e32 v150, vcc, s3, v144
	v_cvt_pk_bf16_f32 v162, v164, v165
	v_cvt_pk_bf16_f32 v163, v166, v163
	v_pk_mul_f32 v[164:165], v[34:35], v[0:1] op_sel_hi:[1,0]
	s_nop 0
	v_addc_co_u32_e32 v151, vcc, 0, v145, vcc
	global_store_dwordx4 v[150:151], v[160:163], off sc1
	v_pk_mul_f32 v[150:151], v[40:41], v[0:1] op_sel_hi:[1,0]
	v_max_f32_e32 v159, 0, v164
	v_pk_mul_f32 v[160:161], v[38:39], v[0:1] op_sel_hi:[1,0]
	v_pk_mul_f32 v[162:163], v[36:37], v[0:1] op_sel_hi:[1,0]
	v_max_f32_e32 v0, 0, v160
	v_max_f32_e32 v160, 0, v161
	v_max_f32_e32 v161, 0, v165
	v_mul_f32_e32 v164, v161, v161
	v_max_f32_e32 v161, 0, v162
	v_mul_f32_e32 v165, v161, v161
	v_max_f32_e32 v161, 0, v163
	v_mul_f32_e32 v160, v160, v160
	v_max_f32_e32 v150, 0, v150
	v_max_f32_e32 v151, 0, v151
	v_mul_f32_e32 v163, v161, v161
	v_mul_f32_e32 v0, v0, v0
	v_mul_f32_e32 v159, v159, v159
	v_mul_f32_e32 v150, v150, v150
	v_mul_f32_e32 v151, v151, v151
	v_cvt_pk_bf16_f32 v160, v0, v160
	v_cvt_pk_bf16_f32 v161, v150, v151
	v_cvt_pk_bf16_f32 v162, v159, v164
	v_cvt_pk_bf16_f32 v163, v165, v163
	global_store_dwordx4 v[148:149], v[160:163], off offset:256 sc1
	s_mov_b32 s3, 0x140000
	v_lshl_add_u64 v[148:149], v[144:145], 0, s[8:9]
	s_mov_b64 s[8:9], 0x160000
	v_fmamk_f32 v0, v208, 0x3a800000, v139
	v_rsq_f32_e32 v0, v0
	s_nop 0
	v_pk_mul_f32 v[160:161], v[30:31], v[0:1] op_sel_hi:[1,0]
	v_pk_mul_f32 v[164:165], v[26:27], v[0:1] op_sel_hi:[1,0]
	v_max_f32_e32 v159, 0, v160
	v_max_f32_e32 v160, 0, v164
	v_pk_mul_f32 v[150:151], v[32:33], v[0:1] op_sel_hi:[1,0]
	v_pk_mul_f32 v[162:163], v[28:29], v[0:1] op_sel_hi:[1,0]
	v_mul_f32_e32 v164, v160, v160
	v_max_f32_e32 v160, 0, v161
	v_max_f32_e32 v161, 0, v165
	v_mul_f32_e32 v165, v161, v161
	v_max_f32_e32 v150, 0, v150
	v_max_f32_e32 v161, 0, v162
	v_mul_f32_e32 v160, v160, v160
	v_mul_f32_e32 v150, v150, v150
	v_mul_f32_e32 v166, v161, v161
	v_max_f32_e32 v151, 0, v151
	v_max_f32_e32 v161, 0, v163
	v_mul_f32_e32 v159, v159, v159
	v_mul_f32_e32 v151, v151, v151
	v_mul_f32_e32 v163, v161, v161
	v_cvt_pk_bf16_f32 v160, v159, v160
	v_cvt_pk_bf16_f32 v161, v150, v151
	v_add_co_u32_e32 v150, vcc, s3, v144
	v_cvt_pk_bf16_f32 v162, v164, v165
	v_cvt_pk_bf16_f32 v163, v166, v163
	v_pk_mul_f32 v[164:165], v[18:19], v[0:1] op_sel_hi:[1,0]
	s_nop 0
	v_addc_co_u32_e32 v151, vcc, 0, v145, vcc
	global_store_dwordx4 v[150:151], v[160:163], off sc1
	v_pk_mul_f32 v[150:151], v[24:25], v[0:1] op_sel_hi:[1,0]
	v_max_f32_e32 v159, 0, v164
	v_pk_mul_f32 v[160:161], v[22:23], v[0:1] op_sel_hi:[1,0]
	v_pk_mul_f32 v[162:163], v[20:21], v[0:1] op_sel_hi:[1,0]
	v_max_f32_e32 v0, 0, v160
	v_max_f32_e32 v160, 0, v161
	v_max_f32_e32 v161, 0, v165
	v_mul_f32_e32 v164, v161, v161
	v_max_f32_e32 v161, 0, v162
	v_mul_f32_e32 v165, v161, v161
	v_max_f32_e32 v161, 0, v163
	v_mul_f32_e32 v160, v160, v160
	v_max_f32_e32 v150, 0, v150
	v_max_f32_e32 v151, 0, v151
	v_mul_f32_e32 v163, v161, v161
	v_mul_f32_e32 v0, v0, v0
	v_mul_f32_e32 v159, v159, v159
	v_mul_f32_e32 v150, v150, v150
	v_mul_f32_e32 v151, v151, v151
	v_cvt_pk_bf16_f32 v160, v0, v160
	v_cvt_pk_bf16_f32 v161, v150, v151
	v_cvt_pk_bf16_f32 v162, v159, v164
	v_cvt_pk_bf16_f32 v163, v165, v163
	global_store_dwordx4 v[148:149], v[160:163], off offset:256 sc1
	s_mov_b32 s3, 0x160000
	v_lshl_add_u64 v[146:147], v[144:145], 0, s[8:9]
	v_add_co_u32_e32 v144, vcc, s3, v144
	v_fmamk_f32 v0, v209, 0x3a800000, v139
	v_rsq_f32_e32 v0, v0
	v_addc_co_u32_e32 v145, vcc, 0, v145, vcc
	v_pk_mul_f32 v[148:149], v[16:17], v[0:1] op_sel_hi:[1,0]
	v_pk_mul_f32 v[150:151], v[14:15], v[0:1] op_sel_hi:[1,0]
	v_pk_mul_f32 v[160:161], v[12:13], v[0:1] op_sel_hi:[1,0]
	v_pk_mul_f32 v[162:163], v[10:11], v[0:1] op_sel_hi:[1,0]
	v_max_f32_e32 v148, 0, v148
	v_max_f32_e32 v150, 0, v150
	v_max_f32_e32 v159, 0, v162
	v_max_f32_e32 v151, 0, v151
	v_max_f32_e32 v162, 0, v163
	v_max_f32_e32 v160, 0, v160
	v_mul_f32_e32 v163, v148, v148
	v_max_f32_e32 v148, 0, v149
	v_max_f32_e32 v149, 0, v161
	v_mul_f32_e32 v150, v150, v150
	v_mul_f32_e32 v151, v151, v151
	v_mul_f32_e32 v160, v160, v160
	v_mul_f32_e32 v161, v148, v148
	v_mul_f32_e32 v164, v149, v149
	v_cvt_pk_bf16_f32 v148, v150, v151
	v_cvt_pk_bf16_f32 v149, v163, v161
	v_mul_f32_e32 v159, v159, v159
	v_mul_f32_e32 v162, v162, v162
	v_cvt_pk_bf16_f32 v150, v159, v162
	v_cvt_pk_bf16_f32 v151, v160, v164
	global_store_dwordx4 v[144:145], v[148:151], off sc1
	v_pk_mul_f32 v[160:161], v[2:3], v[0:1] op_sel_hi:[1,0]
	v_pk_mul_f32 v[144:145], v[8:9], v[0:1] op_sel_hi:[1,0]
	v_pk_mul_f32 v[148:149], v[6:7], v[0:1] op_sel_hi:[1,0]
	v_pk_mul_f32 v[150:151], v[4:5], v[0:1] op_sel_hi:[1,0]
	v_max_f32_e32 v0, 0, v148
	v_max_f32_e32 v148, 0, v160
	v_mul_f32_e32 v159, v148, v148
	v_max_f32_e32 v148, 0, v149
	v_max_f32_e32 v149, 0, v161
	v_mul_f32_e32 v160, v149, v149
	v_max_f32_e32 v149, 0, v150
	v_mul_f32_e32 v161, v149, v149
	v_max_f32_e32 v149, 0, v151
	v_mul_f32_e32 v148, v148, v148
	v_max_f32_e32 v144, 0, v144
	v_max_f32_e32 v145, 0, v145
	v_mul_f32_e32 v151, v149, v149
	v_mul_f32_e32 v0, v0, v0
	v_mul_f32_e32 v144, v144, v144
	v_mul_f32_e32 v145, v145, v145
	v_cvt_pk_bf16_f32 v148, v0, v148
	v_cvt_pk_bf16_f32 v149, v144, v145
	v_cvt_pk_bf16_f32 v150, v159, v160
	v_cvt_pk_bf16_f32 v151, v161, v151
	global_store_dwordx4 v[146:147], v[148:151], off offset:256 sc1
